# v19 + hand-written gate/up (SwiGLU) GEMM epilogue: all row-stat loads issued together, rsqrt+Newton rstd, batched exp/rcp, half the instructions
# speedup vs baseline: 1.0248x; 1.0201x over previous
; __device__ __forceinline__ void load_rstd8(const float* ssq, const float* ssqc, int row0, int fq, float (&rs)[2][4]) {
;     const bool isc = row0 >= ML;
; #pragma unroll
;     for (int ai = 0; ai < 2; ++ai)
; #pragma unroll
;         for (int m = 0; m < 4; ++m) {
;             const int row = row0 + ai * HALF + m * 16;
;             float s;
;             if (!isc) { const f32x4 a = *(const f32x4*)(ssq + ((size_t)(2 * fq) * MT + row) * 4), b = *(const f32x4*)(ssq + ((size_t)(2 * fq + 1) * MT + row) * 4);
;                 s = ((a[0] + a[1]) + (a[2] + a[3])) + ((b[0] + b[1]) + (b[2] + b[3])); }
;     __device__ __forceinline__ void operator()(const f32x4 (&acc)[2][2][4][2], const Unit& u, int wr, int wc, int fr_, int fq_) const {
;     ...
;         const int row0 = u.pm * BM + wr * 64 + fr, v = vec_of_panel(u.pm);
;         float rs[2][4]; load_rstd8(ssq, ssqc, row0, fq, rs);
;         const int colb = u.pn * BM + wc * 32 + 8 * fq;
;         f32x4 sh[2][2];
; #pragma unroll
;         for (int bj = 0; bj < 2; ++bj)
; #pragma unroll
;             for (int n = 0; n < 2; ++n) sh[bj][n] = *(const f32x4*)(shw + (size_t)v * GU + colb + bj * HALF + 4 * n);
.LBB0_1161:
	v_readlane_b32 s90, v253, 3
	v_readlane_b32 s91, v253, 4
	s_lshl_b32 s53, s80, 8
	s_add_u32 s53, s53, s81
	v_add_u32_e32 v0, s53, v183
	s_nop 0
	s_load_dwordx2 s[62:63], s[90:91], 0xd8
	s_lshl_b32 s55, s78, 8
	s_add_u32 s55, s55, s86
	v_lshl_add_u32 v186, v185, 3, s55
	v_lshlrev_b32_e32 v186, 2, v186
	s_lshl_b32 s73, s78, 7
	s_add_u32 s73, s73, s86
	v_lshl_add_u32 v192, v185, 3, s73
	s_mov_b32 s74, 0x1600
	v_mul_lo_u32 v188, v0, s74
	v_add_u32_e32 v188, v188, v192
	v_lshlrev_b32_e32 v188, 1, v188
	v_xor_b32_e32 v189, 16, v201
	v_lshlrev_b32_e32 v189, 2, v189
	v_xor_b32_e32 v190, 32, v201
	v_lshlrev_b32_e32 v190, 2, v190
	s_cmp_ge_u32 s80, 16
	s_cselect_b32 s73, 1, 0
	s_cmp_ge_u32 s80, 32
	s_cselect_b32 s73, 2, s73
	s_waitcnt lgkmcnt(0)
	s_add_u32 s12, s62, 0xf8a0000
	s_addc_u32 s13, s63, 0
	s_add_u32 s84, s62, 0x15bde000
	s_addc_u32 s85, s63, 0
	s_mul_i32 s74, s76, 0x21000
	s_mul_i32 s73, s73, 0xb000
	s_add_u32 s74, s74, s73
	s_add_u32 s84, s84, s74
	s_addc_u32 s85, s85, 0
	s_cmp_ge_u32 s80, 32
	s_cbranch_scc1 .Lepigu_ctx
	s_add_u32 s82, s62, 0x6700000
	s_addc_u32 s83, s63, 0
	v_mul_u32_u24_e32 v192, 0x4400, v185
	v_add_u32_e32 v192, v192, v0
	v_lshlrev_b32_e32 v182, 4, v192
	v_add_u32_e32 v184, 0x22000, v182
	global_load_dwordx4 v[202:205], v182, s[82:83]
	global_load_dwordx4 v[206:209], v184, s[82:83]
	global_load_dwordx4 v[210:213], v182, s[82:83] offset:256
	global_load_dwordx4 v[214:217], v184, s[82:83] offset:256
	global_load_dwordx4 v[218:221], v182, s[82:83] offset:512
	global_load_dwordx4 v[222:225], v184, s[82:83] offset:512
	global_load_dwordx4 v[228:231], v182, s[82:83] offset:768
	global_load_dwordx4 v[232:235], v184, s[82:83] offset:768
	global_load_dwordx4 v[158:161], v182, s[82:83] offset:2048
	global_load_dwordx4 v[162:165], v184, s[82:83] offset:2048
	global_load_dwordx4 v[166:169], v182, s[82:83] offset:2304
	global_load_dwordx4 v[170:173], v184, s[82:83] offset:2304
	global_load_dwordx4 v[174:177], v182, s[82:83] offset:2560
	global_load_dwordx4 v[178:181], v184, s[82:83] offset:2560
	global_load_dwordx4 v[130:133], v182, s[82:83] offset:2816
	global_load_dwordx4 v[134:137], v184, s[82:83] offset:2816
	global_load_dwordx4 v[138:141], v186, s[84:85]
	global_load_dwordx4 v[142:145], v186, s[84:85] offset:16
	global_load_dwordx4 v[240:243], v186, s[84:85] offset:512
	global_load_dwordx4 v[244:247], v186, s[84:85] offset:528
	s_waitcnt vmcnt(19)
	v_add_f32_e32 v202, v202, v203
	v_add_f32_e32 v204, v204, v205
	s_waitcnt vmcnt(18)
	v_add_f32_e32 v206, v206, v207
	v_add_f32_e32 v208, v208, v209
	v_add_f32_e32 v202, v202, v204
	v_add_f32_e32 v206, v206, v208
	v_add_f32_e32 v202, v202, v206
	s_waitcnt vmcnt(17)
	v_add_f32_e32 v210, v210, v211
	v_add_f32_e32 v212, v212, v213
	s_waitcnt vmcnt(16)
	v_add_f32_e32 v214, v214, v215
	v_add_f32_e32 v216, v216, v217
	v_add_f32_e32 v210, v210, v212
	v_add_f32_e32 v214, v214, v216
	v_add_f32_e32 v210, v210, v214
	s_waitcnt vmcnt(15)
	v_add_f32_e32 v218, v218, v219
	v_add_f32_e32 v220, v220, v221
	s_waitcnt vmcnt(14)
	v_add_f32_e32 v222, v222, v223
	v_add_f32_e32 v224, v224, v225
	v_add_f32_e32 v218, v218, v220
	v_add_f32_e32 v222, v222, v224
	v_add_f32_e32 v218, v218, v222
	s_waitcnt vmcnt(13)
	v_add_f32_e32 v228, v228, v229
	v_add_f32_e32 v230, v230, v231
	s_waitcnt vmcnt(12)
	v_add_f32_e32 v232, v232, v233
	v_add_f32_e32 v234, v234, v235
	v_add_f32_e32 v228, v228, v230
	v_add_f32_e32 v232, v232, v234
	v_add_f32_e32 v228, v228, v232
	s_waitcnt vmcnt(11)
	v_add_f32_e32 v158, v158, v159
	v_add_f32_e32 v160, v160, v161
	s_waitcnt vmcnt(10)
	v_add_f32_e32 v162, v162, v163
	v_add_f32_e32 v164, v164, v165
	v_add_f32_e32 v158, v158, v160
	v_add_f32_e32 v162, v162, v164
	v_add_f32_e32 v158, v158, v162
	s_waitcnt vmcnt(9)
	v_add_f32_e32 v166, v166, v167
	v_add_f32_e32 v168, v168, v169
	s_waitcnt vmcnt(8)
	v_add_f32_e32 v170, v170, v171
	v_add_f32_e32 v172, v172, v173
	v_add_f32_e32 v166, v166, v168
	v_add_f32_e32 v170, v170, v172
	v_add_f32_e32 v166, v166, v170
	s_waitcnt vmcnt(7)
	v_add_f32_e32 v174, v174, v175
	v_add_f32_e32 v176, v176, v177
	s_waitcnt vmcnt(6)
	v_add_f32_e32 v178, v178, v179
	v_add_f32_e32 v180, v180, v181
	v_add_f32_e32 v174, v174, v176
	v_add_f32_e32 v178, v178, v180
	v_add_f32_e32 v174, v174, v178
	s_waitcnt vmcnt(5)
	v_add_f32_e32 v130, v130, v131
	v_add_f32_e32 v132, v132, v133
	s_waitcnt vmcnt(4)
	v_add_f32_e32 v134, v134, v135
	v_add_f32_e32 v136, v136, v137
	v_add_f32_e32 v130, v130, v132
	v_add_f32_e32 v134, v134, v136
	v_add_f32_e32 v130, v130, v134
	s_branch .Lepigu_join
; __device__ __forceinline__ void load_rstd8(const float* ssq, const float* ssqc, int row0, int fq, float (&rs)[2][4]) {
;     ...
;             else { s = 0.f;
; #pragma unroll
;                 for (int j = 0; j < 8; ++j) s += ssqc[(size_t)(fq * 8 + j) * MC + (row - ML)]; }
;     __device__ __forceinline__ void operator()(const f32x4 (&acc)[2][2][4][2], const Unit& u, int wr, int wc, int fr_, int fq_) const {
;     ...
;         f32x4 sh[2][2];
; #pragma unroll
;         for (int bj = 0; bj < 2; ++bj)
; #pragma unroll
;             for (int n = 0; n < 2; ++n) sh[bj][n] = *(const f32x4*)(shw + (size_t)v * GU + colb + bj * HALF + 4 * n);
.Lepigu_ctx:
	s_add_u32 s82, s62, 0x6810000
	s_addc_u32 s83, s63, 0
	v_mul_u32_u24_e32 v192, 0x1000, v185
	v_add_u32_e32 v192, v192, v0
	v_add_u32_e32 v192, 0xffffe000, v192
	v_lshlrev_b32_e32 v182, 2, v192
	v_add_u32_e32 v184, 0x1000, v182
	v_add_u32_e32 v194, 0x2000, v182
	v_add_u32_e32 v196, 0x3000, v182
	global_load_dword v202, v182, s[82:83]
	global_load_dword v203, v182, s[82:83] offset:2048
	global_load_dword v204, v184, s[82:83]
	global_load_dword v205, v184, s[82:83] offset:2048
	global_load_dword v206, v194, s[82:83]
	global_load_dword v207, v194, s[82:83] offset:2048
	global_load_dword v208, v196, s[82:83]
	global_load_dword v209, v196, s[82:83] offset:2048
	global_load_dword v210, v182, s[82:83] offset:64
	global_load_dword v211, v182, s[82:83] offset:2112
	global_load_dword v212, v184, s[82:83] offset:64
	global_load_dword v213, v184, s[82:83] offset:2112
	global_load_dword v214, v194, s[82:83] offset:64
	global_load_dword v215, v194, s[82:83] offset:2112
	global_load_dword v216, v196, s[82:83] offset:64
	global_load_dword v217, v196, s[82:83] offset:2112
	global_load_dword v218, v182, s[82:83] offset:128
	global_load_dword v219, v182, s[82:83] offset:2176
	global_load_dword v220, v184, s[82:83] offset:128
	global_load_dword v221, v184, s[82:83] offset:2176
	global_load_dword v222, v194, s[82:83] offset:128
	global_load_dword v223, v194, s[82:83] offset:2176
	global_load_dword v224, v196, s[82:83] offset:128
	global_load_dword v225, v196, s[82:83] offset:2176
	global_load_dword v228, v182, s[82:83] offset:192
	global_load_dword v229, v182, s[82:83] offset:2240
	global_load_dword v230, v184, s[82:83] offset:192
	global_load_dword v231, v184, s[82:83] offset:2240
	global_load_dword v232, v194, s[82:83] offset:192
	global_load_dword v233, v194, s[82:83] offset:2240
	global_load_dword v234, v196, s[82:83] offset:192
	global_load_dword v235, v196, s[82:83] offset:2240
	global_load_dword v158, v182, s[82:83] offset:512
	global_load_dword v159, v182, s[82:83] offset:2560
	global_load_dword v160, v184, s[82:83] offset:512
	global_load_dword v161, v184, s[82:83] offset:2560
	global_load_dword v162, v194, s[82:83] offset:512
	global_load_dword v163, v194, s[82:83] offset:2560
	global_load_dword v164, v196, s[82:83] offset:512
	global_load_dword v165, v196, s[82:83] offset:2560
	global_load_dword v166, v182, s[82:83] offset:576
	global_load_dword v167, v182, s[82:83] offset:2624
	global_load_dword v168, v184, s[82:83] offset:576
	global_load_dword v169, v184, s[82:83] offset:2624
	global_load_dword v170, v194, s[82:83] offset:576
	global_load_dword v171, v194, s[82:83] offset:2624
	global_load_dword v172, v196, s[82:83] offset:576
	global_load_dword v173, v196, s[82:83] offset:2624
	global_load_dword v174, v182, s[82:83] offset:640
	global_load_dword v175, v182, s[82:83] offset:2688
	global_load_dword v176, v184, s[82:83] offset:640
	global_load_dword v177, v184, s[82:83] offset:2688
	global_load_dword v178, v194, s[82:83] offset:640
	global_load_dword v179, v194, s[82:83] offset:2688
	global_load_dword v180, v196, s[82:83] offset:640
	global_load_dword v181, v196, s[82:83] offset:2688
	global_load_dword v130, v182, s[82:83] offset:704
	global_load_dword v131, v182, s[82:83] offset:2752
	global_load_dword v132, v184, s[82:83] offset:704
	global_load_dword v133, v184, s[82:83] offset:2752
	global_load_dword v134, v194, s[82:83] offset:704
	global_load_dword v135, v194, s[82:83] offset:2752
	global_load_dword v136, v196, s[82:83] offset:704
	global_load_dword v137, v196, s[82:83] offset:2752
	global_load_dwordx4 v[138:141], v186, s[84:85]
	global_load_dwordx4 v[142:145], v186, s[84:85] offset:16
	global_load_dwordx4 v[240:243], v186, s[84:85] offset:512
	global_load_dwordx4 v[244:247], v186, s[84:85] offset:528
	s_waitcnt vmcnt(63)
	v_add_f32_e32 v202, v202, v203
	v_add_f32_e32 v202, v202, v204
	v_add_f32_e32 v202, v202, v205
	v_add_f32_e32 v202, v202, v206
	s_waitcnt vmcnt(62)
	v_add_f32_e32 v202, v202, v207
	s_waitcnt vmcnt(61)
	v_add_f32_e32 v202, v202, v208
	s_waitcnt vmcnt(60)
	v_add_f32_e32 v202, v202, v209
	s_waitcnt vmcnt(58)
	v_add_f32_e32 v210, v210, v211
	s_waitcnt vmcnt(57)
	v_add_f32_e32 v210, v210, v212
	s_waitcnt vmcnt(56)
	v_add_f32_e32 v210, v210, v213
	s_waitcnt vmcnt(55)
	v_add_f32_e32 v210, v210, v214
	s_waitcnt vmcnt(54)
	v_add_f32_e32 v210, v210, v215
	s_waitcnt vmcnt(53)
	v_add_f32_e32 v210, v210, v216
	s_waitcnt vmcnt(52)
	v_add_f32_e32 v210, v210, v217
	s_waitcnt vmcnt(50)
	v_add_f32_e32 v218, v218, v219
	s_waitcnt vmcnt(49)
	v_add_f32_e32 v218, v218, v220
	s_waitcnt vmcnt(48)
	v_add_f32_e32 v218, v218, v221
	s_waitcnt vmcnt(47)
	v_add_f32_e32 v218, v218, v222
	s_waitcnt vmcnt(46)
	v_add_f32_e32 v218, v218, v223
	s_waitcnt vmcnt(45)
	v_add_f32_e32 v218, v218, v224
	s_waitcnt vmcnt(44)
	v_add_f32_e32 v218, v218, v225
	s_waitcnt vmcnt(42)
	v_add_f32_e32 v228, v228, v229
	s_waitcnt vmcnt(41)
	v_add_f32_e32 v228, v228, v230
	s_waitcnt vmcnt(40)
	v_add_f32_e32 v228, v228, v231
	s_waitcnt vmcnt(39)
	v_add_f32_e32 v228, v228, v232
	s_waitcnt vmcnt(38)
	v_add_f32_e32 v228, v228, v233
	s_waitcnt vmcnt(37)
	v_add_f32_e32 v228, v228, v234
	s_waitcnt vmcnt(36)
	v_add_f32_e32 v228, v228, v235
	s_waitcnt vmcnt(34)
	v_add_f32_e32 v158, v158, v159
	s_waitcnt vmcnt(33)
	v_add_f32_e32 v158, v158, v160
	s_waitcnt vmcnt(32)
	v_add_f32_e32 v158, v158, v161
	s_waitcnt vmcnt(31)
	v_add_f32_e32 v158, v158, v162
	s_waitcnt vmcnt(30)
	v_add_f32_e32 v158, v158, v163
	s_waitcnt vmcnt(29)
	v_add_f32_e32 v158, v158, v164
	s_waitcnt vmcnt(28)
	v_add_f32_e32 v158, v158, v165
	s_waitcnt vmcnt(26)
	v_add_f32_e32 v166, v166, v167
	s_waitcnt vmcnt(25)
	v_add_f32_e32 v166, v166, v168
	s_waitcnt vmcnt(24)
	v_add_f32_e32 v166, v166, v169
	s_waitcnt vmcnt(23)
	v_add_f32_e32 v166, v166, v170
	s_waitcnt vmcnt(22)
	v_add_f32_e32 v166, v166, v171
	s_waitcnt vmcnt(21)
	v_add_f32_e32 v166, v166, v172
	s_waitcnt vmcnt(20)
	v_add_f32_e32 v166, v166, v173
	s_waitcnt vmcnt(18)
	v_add_f32_e32 v174, v174, v175
	s_waitcnt vmcnt(17)
	v_add_f32_e32 v174, v174, v176
	s_waitcnt vmcnt(16)
	v_add_f32_e32 v174, v174, v177
	s_waitcnt vmcnt(15)
	v_add_f32_e32 v174, v174, v178
	s_waitcnt vmcnt(14)
	v_add_f32_e32 v174, v174, v179
	s_waitcnt vmcnt(13)
	v_add_f32_e32 v174, v174, v180
	s_waitcnt vmcnt(12)
	v_add_f32_e32 v174, v174, v181
	s_waitcnt vmcnt(10)
	v_add_f32_e32 v130, v130, v131
	s_waitcnt vmcnt(9)
	v_add_f32_e32 v130, v130, v132
	s_waitcnt vmcnt(8)
	v_add_f32_e32 v130, v130, v133
	s_waitcnt vmcnt(7)
	v_add_f32_e32 v130, v130, v134
	s_waitcnt vmcnt(6)
	v_add_f32_e32 v130, v130, v135
	s_waitcnt vmcnt(5)
	v_add_f32_e32 v130, v130, v136
	s_waitcnt vmcnt(4)
	v_add_f32_e32 v130, v130, v137
; __device__ __forceinline__ unsigned pk2(float lo, float hi) { unsigned r; asm("v_cvt_pk_bf16_f32 %0, %1, %2" : "=v"(r) : "v"(lo), "v"(hi)); return r; }
; __device__ __forceinline__ void load_rstd8(const float* ssq, const float* ssqc, int row0, int fq, float (&rs)[2][4]) {
;     ...
;             s += __shfl_xor(s, 16); s += __shfl_xor(s, 32);
;             rs[ai][m] = 1.0f / sqrtf(s * (1.0f / D) + EPS);
;     __device__ __forceinline__ void operator()(const f32x4 (&acc)[2][2][4][2], const Unit& u, int wr, int wc, int fr_, int fq_) const {
;     ...
;             for (int m = 0; m < 4; ++m) { const int row = row0 + ai * HALF + m * 16; const float r = rs[ai][m];
;                 unsigned hw[4];
; #pragma unroll
;                 for (int n = 0; n < 2; ++n) { const f32x4 g = acc[ai][0][m][n] * r + sh[0][n], up = acc[ai][1][m][n] * r + sh[1][n];
;                     float h[4];
; #pragma unroll
;                     for (int e = 0; e < 4; ++e) h[e] = g[e] * __builtin_amdgcn_rcpf(1.0f + __builtin_amdgcn_exp2f(-g[e] * LOG2E)) * up[e];
;                     hw[2 * n] = pk2(h[0], h[1]); hw[2 * n + 1] = pk2(h[2], h[3]); }
;                 u32x4 w; w.x = hw[0]; w.y = hw[1]; w.z = hw[2]; w.w = hw[3];
;                 *(u32x4*)(HB + (size_t)row * FF + u.pn * HALF + wc * 32 + 8 * fq) = w; }
.Lepigu_join:
	s_waitcnt vmcnt(0)
	ds_bpermute_b32 v192, v189, v202
	ds_bpermute_b32 v194, v189, v210
	ds_bpermute_b32 v196, v189, v218
	ds_bpermute_b32 v198, v189, v228
	ds_bpermute_b32 v200, v189, v158
	ds_bpermute_b32 v226, v189, v166
	ds_bpermute_b32 v236, v189, v174
	ds_bpermute_b32 v239, v189, v130
	s_waitcnt lgkmcnt(7)
	v_add_f32_e32 v202, v202, v192
	s_waitcnt lgkmcnt(6)
	v_add_f32_e32 v210, v210, v194
	s_waitcnt lgkmcnt(5)
	v_add_f32_e32 v218, v218, v196
	s_waitcnt lgkmcnt(4)
	v_add_f32_e32 v228, v228, v198
	s_waitcnt lgkmcnt(3)
	v_add_f32_e32 v158, v158, v200
	s_waitcnt lgkmcnt(2)
	v_add_f32_e32 v166, v166, v226
	s_waitcnt lgkmcnt(1)
	v_add_f32_e32 v174, v174, v236
	s_waitcnt lgkmcnt(0)
	v_add_f32_e32 v130, v130, v239
	ds_bpermute_b32 v192, v190, v202
	ds_bpermute_b32 v194, v190, v210
	ds_bpermute_b32 v196, v190, v218
	ds_bpermute_b32 v198, v190, v228
	ds_bpermute_b32 v200, v190, v158
	ds_bpermute_b32 v226, v190, v166
	ds_bpermute_b32 v236, v190, v174
	ds_bpermute_b32 v239, v190, v130
	s_waitcnt lgkmcnt(7)
	v_add_f32_e32 v202, v202, v192
	s_waitcnt lgkmcnt(6)
	v_add_f32_e32 v210, v210, v194
	s_waitcnt lgkmcnt(5)
	v_add_f32_e32 v218, v218, v196
	s_waitcnt lgkmcnt(4)
	v_add_f32_e32 v228, v228, v198
	s_waitcnt lgkmcnt(3)
	v_add_f32_e32 v158, v158, v200
	s_waitcnt lgkmcnt(2)
	v_add_f32_e32 v166, v166, v226
	s_waitcnt lgkmcnt(1)
	v_add_f32_e32 v174, v174, v236
	s_waitcnt lgkmcnt(0)
	v_add_f32_e32 v130, v130, v239
	v_mov_b32_e32 v184, 0x358637bd
	v_fmamk_f32 v202, v202, 0x3a000000, v184
	v_fmamk_f32 v210, v210, 0x3a000000, v184
	v_fmamk_f32 v218, v218, 0x3a000000, v184
	v_fmamk_f32 v228, v228, 0x3a000000, v184
	v_fmamk_f32 v158, v158, 0x3a000000, v184
	v_fmamk_f32 v166, v166, 0x3a000000, v184
	v_fmamk_f32 v174, v174, 0x3a000000, v184
	v_fmamk_f32 v130, v130, 0x3a000000, v184
	v_rsq_f32_e32 v206, v202
	v_rsq_f32_e32 v214, v210
	v_rsq_f32_e32 v222, v218
	v_rsq_f32_e32 v232, v228
	v_rsq_f32_e32 v162, v158
	v_rsq_f32_e32 v170, v166
	v_rsq_f32_e32 v178, v174
	v_rsq_f32_e32 v134, v130
	v_mul_f32_e32 v192, v202, v206
	v_mul_f32_e32 v194, v210, v214
	v_mul_f32_e32 v196, v218, v222
	v_mul_f32_e32 v198, v228, v232
	v_mul_f32_e32 v200, v158, v162
	v_mul_f32_e32 v226, v166, v170
	v_mul_f32_e32 v236, v174, v178
	v_mul_f32_e32 v239, v130, v134
	v_fma_f32 v192, -v192, v206, 1.0
	v_fma_f32 v194, -v194, v214, 1.0
	v_fma_f32 v196, -v196, v222, 1.0
	v_fma_f32 v198, -v198, v232, 1.0
	v_fma_f32 v200, -v200, v162, 1.0
	v_fma_f32 v226, -v226, v170, 1.0
	v_fma_f32 v236, -v236, v178, 1.0
	v_fma_f32 v239, -v239, v134, 1.0
	v_mul_f32_e32 v202, 0.5, v206
	v_mul_f32_e32 v210, 0.5, v214
	v_mul_f32_e32 v218, 0.5, v222
	v_mul_f32_e32 v228, 0.5, v232
	v_mul_f32_e32 v158, 0.5, v162
	v_mul_f32_e32 v166, 0.5, v170
	v_mul_f32_e32 v174, 0.5, v178
	v_mul_f32_e32 v130, 0.5, v134
	v_fma_f32 v206, v202, v192, v206
	v_fma_f32 v214, v210, v194, v214
	v_fma_f32 v222, v218, v196, v222
	v_fma_f32 v232, v228, v198, v232
	v_fma_f32 v162, v158, v200, v162
	v_fma_f32 v170, v166, v226, v170
	v_fma_f32 v178, v174, v236, v178
	v_fma_f32 v134, v130, v239, v134
	v_pk_fma_f32 v[126:127], v[126:127], v[206:207], v[138:139] op_sel_hi:[1,0,1]
	v_pk_fma_f32 v[122:123], v[122:123], v[206:207], v[240:241] op_sel_hi:[1,0,1]
	v_pk_fma_f32 v[128:129], v[128:129], v[206:207], v[140:141] op_sel_hi:[1,0,1]
	v_pk_fma_f32 v[124:125], v[124:125], v[206:207], v[242:243] op_sel_hi:[1,0,1]
	v_pk_fma_f32 v[118:119], v[118:119], v[206:207], v[142:143] op_sel_hi:[1,0,1]
	v_pk_fma_f32 v[114:115], v[114:115], v[206:207], v[244:245] op_sel_hi:[1,0,1]
	v_pk_fma_f32 v[120:121], v[120:121], v[206:207], v[144:145] op_sel_hi:[1,0,1]
	v_pk_fma_f32 v[116:117], v[116:117], v[206:207], v[246:247] op_sel_hi:[1,0,1]
	v_mul_f32_e32 v192, 0xbfb8aa3b, v126
	v_mul_f32_e32 v194, 0xbfb8aa3b, v127
	v_mul_f32_e32 v196, 0xbfb8aa3b, v128
	v_mul_f32_e32 v198, 0xbfb8aa3b, v129
	v_mul_f32_e32 v200, 0xbfb8aa3b, v118
	v_mul_f32_e32 v226, 0xbfb8aa3b, v119
	v_mul_f32_e32 v236, 0xbfb8aa3b, v120
	v_mul_f32_e32 v239, 0xbfb8aa3b, v121
	v_exp_f32_e32 v192, v192
	v_exp_f32_e32 v194, v194
	v_exp_f32_e32 v196, v196
	v_exp_f32_e32 v198, v198
	v_exp_f32_e32 v200, v200
	v_exp_f32_e32 v226, v226
	v_exp_f32_e32 v236, v236
	v_exp_f32_e32 v239, v239
	v_add_f32_e32 v192, 1.0, v192
	v_add_f32_e32 v194, 1.0, v194
	v_add_f32_e32 v196, 1.0, v196
	v_add_f32_e32 v198, 1.0, v198
	v_add_f32_e32 v200, 1.0, v200
	v_add_f32_e32 v226, 1.0, v226
	v_add_f32_e32 v236, 1.0, v236
	v_add_f32_e32 v239, 1.0, v239
	v_rcp_f32_e32 v192, v192
	v_rcp_f32_e32 v194, v194
	v_rcp_f32_e32 v196, v196
	v_rcp_f32_e32 v198, v198
	v_rcp_f32_e32 v200, v200
	v_rcp_f32_e32 v226, v226
	v_rcp_f32_e32 v236, v236
	v_rcp_f32_e32 v239, v239
	v_mul_f32_e32 v126, v126, v192
	v_mul_f32_e32 v127, v127, v194
	v_mul_f32_e32 v128, v128, v196
	v_mul_f32_e32 v129, v129, v198
	v_mul_f32_e32 v118, v118, v200
	v_mul_f32_e32 v119, v119, v226
	v_mul_f32_e32 v120, v120, v236
	v_mul_f32_e32 v121, v121, v239
	v_mul_f32_e32 v126, v122, v126
	v_mul_f32_e32 v127, v123, v127
	v_mul_f32_e32 v128, v124, v128
	v_mul_f32_e32 v129, v125, v129
	v_mul_f32_e32 v118, v114, v118
	v_mul_f32_e32 v119, v115, v119
	v_mul_f32_e32 v120, v116, v120
	v_mul_f32_e32 v121, v117, v121
	v_cvt_pk_bf16_f32 v202, v126, v127
	v_cvt_pk_bf16_f32 v203, v128, v129
	v_cvt_pk_bf16_f32 v204, v118, v119
	v_cvt_pk_bf16_f32 v205, v120, v121
	global_store_dwordx4 v188, v[202:205], s[12:13]
	v_add_u32_e32 v188, 0x2c000, v188
	v_pk_fma_f32 v[110:111], v[110:111], v[214:215], v[138:139] op_sel_hi:[1,0,1]
	v_pk_fma_f32 v[106:107], v[106:107], v[214:215], v[240:241] op_sel_hi:[1,0,1]
	v_pk_fma_f32 v[112:113], v[112:113], v[214:215], v[140:141] op_sel_hi:[1,0,1]
; __device__ __forceinline__ unsigned pk2(float lo, float hi) { unsigned r; asm("v_cvt_pk_bf16_f32 %0, %1, %2" : "=v"(r) : "v"(lo), "v"(hi)); return r; }
;     __device__ __forceinline__ void operator()(const f32x4 (&acc)[2][2][4][2], const Unit& u, int wr, int wc, int fr_, int fq_) const {
;     ...
;             for (int m = 0; m < 4; ++m) { const int row = row0 + ai * HALF + m * 16; const float r = rs[ai][m];
;                 unsigned hw[4];
; #pragma unroll
;                 for (int n = 0; n < 2; ++n) { const f32x4 g = acc[ai][0][m][n] * r + sh[0][n], up = acc[ai][1][m][n] * r + sh[1][n];
;                     float h[4];
; #pragma unroll
;                     for (int e = 0; e < 4; ++e) h[e] = g[e] * __builtin_amdgcn_rcpf(1.0f + __builtin_amdgcn_exp2f(-g[e] * LOG2E)) * up[e];
;                     hw[2 * n] = pk2(h[0], h[1]); hw[2 * n + 1] = pk2(h[2], h[3]); }
;                 u32x4 w; w.x = hw[0]; w.y = hw[1]; w.z = hw[2]; w.w = hw[3];
;                 *(u32x4*)(HB + (size_t)row * FF + u.pn * HALF + wc * 32 + 8 * fq) = w; }
	v_pk_fma_f32 v[108:109], v[108:109], v[214:215], v[242:243] op_sel_hi:[1,0,1]
	v_pk_fma_f32 v[102:103], v[102:103], v[214:215], v[142:143] op_sel_hi:[1,0,1]
	v_pk_fma_f32 v[98:99], v[98:99], v[214:215], v[244:245] op_sel_hi:[1,0,1]
	v_pk_fma_f32 v[104:105], v[104:105], v[214:215], v[144:145] op_sel_hi:[1,0,1]
	v_pk_fma_f32 v[100:101], v[100:101], v[214:215], v[246:247] op_sel_hi:[1,0,1]
	v_mul_f32_e32 v192, 0xbfb8aa3b, v110
	v_mul_f32_e32 v194, 0xbfb8aa3b, v111
	v_mul_f32_e32 v196, 0xbfb8aa3b, v112
	v_mul_f32_e32 v198, 0xbfb8aa3b, v113
	v_mul_f32_e32 v200, 0xbfb8aa3b, v102
	v_mul_f32_e32 v226, 0xbfb8aa3b, v103
	v_mul_f32_e32 v236, 0xbfb8aa3b, v104
	v_mul_f32_e32 v239, 0xbfb8aa3b, v105
	v_exp_f32_e32 v192, v192
	v_exp_f32_e32 v194, v194
	v_exp_f32_e32 v196, v196
	v_exp_f32_e32 v198, v198
	v_exp_f32_e32 v200, v200
	v_exp_f32_e32 v226, v226
	v_exp_f32_e32 v236, v236
	v_exp_f32_e32 v239, v239
	v_add_f32_e32 v192, 1.0, v192
	v_add_f32_e32 v194, 1.0, v194
	v_add_f32_e32 v196, 1.0, v196
	v_add_f32_e32 v198, 1.0, v198
	v_add_f32_e32 v200, 1.0, v200
	v_add_f32_e32 v226, 1.0, v226
	v_add_f32_e32 v236, 1.0, v236
	v_add_f32_e32 v239, 1.0, v239
	v_rcp_f32_e32 v192, v192
	v_rcp_f32_e32 v194, v194
	v_rcp_f32_e32 v196, v196
	v_rcp_f32_e32 v198, v198
	v_rcp_f32_e32 v200, v200
	v_rcp_f32_e32 v226, v226
	v_rcp_f32_e32 v236, v236
	v_rcp_f32_e32 v239, v239
	v_mul_f32_e32 v110, v110, v192
	v_mul_f32_e32 v111, v111, v194
	v_mul_f32_e32 v112, v112, v196
	v_mul_f32_e32 v113, v113, v198
	v_mul_f32_e32 v102, v102, v200
	v_mul_f32_e32 v103, v103, v226
	v_mul_f32_e32 v104, v104, v236
	v_mul_f32_e32 v105, v105, v239
	v_mul_f32_e32 v110, v106, v110
	v_mul_f32_e32 v111, v107, v111
	v_mul_f32_e32 v112, v108, v112
	v_mul_f32_e32 v113, v109, v113
	v_mul_f32_e32 v102, v98, v102
	v_mul_f32_e32 v103, v99, v103
	v_mul_f32_e32 v104, v100, v104
	v_mul_f32_e32 v105, v101, v105
	v_cvt_pk_bf16_f32 v210, v110, v111
	v_cvt_pk_bf16_f32 v211, v112, v113
	v_cvt_pk_bf16_f32 v212, v102, v103
	v_cvt_pk_bf16_f32 v213, v104, v105
	global_store_dwordx4 v188, v[210:213], s[12:13]
	v_add_u32_e32 v188, 0x2c000, v188
	v_pk_fma_f32 v[94:95], v[94:95], v[222:223], v[138:139] op_sel_hi:[1,0,1]
	v_pk_fma_f32 v[90:91], v[90:91], v[222:223], v[240:241] op_sel_hi:[1,0,1]
	v_pk_fma_f32 v[96:97], v[96:97], v[222:223], v[140:141] op_sel_hi:[1,0,1]
	v_pk_fma_f32 v[92:93], v[92:93], v[222:223], v[242:243] op_sel_hi:[1,0,1]
	v_pk_fma_f32 v[86:87], v[86:87], v[222:223], v[142:143] op_sel_hi:[1,0,1]
	v_pk_fma_f32 v[82:83], v[82:83], v[222:223], v[244:245] op_sel_hi:[1,0,1]
	v_pk_fma_f32 v[88:89], v[88:89], v[222:223], v[144:145] op_sel_hi:[1,0,1]
	v_pk_fma_f32 v[84:85], v[84:85], v[222:223], v[246:247] op_sel_hi:[1,0,1]
	v_mul_f32_e32 v192, 0xbfb8aa3b, v94
	v_mul_f32_e32 v194, 0xbfb8aa3b, v95
	v_mul_f32_e32 v196, 0xbfb8aa3b, v96
	v_mul_f32_e32 v198, 0xbfb8aa3b, v97
	v_mul_f32_e32 v200, 0xbfb8aa3b, v86
	v_mul_f32_e32 v226, 0xbfb8aa3b, v87
	v_mul_f32_e32 v236, 0xbfb8aa3b, v88
	v_mul_f32_e32 v239, 0xbfb8aa3b, v89
	v_exp_f32_e32 v192, v192
	v_exp_f32_e32 v194, v194
	v_exp_f32_e32 v196, v196
	v_exp_f32_e32 v198, v198
	v_exp_f32_e32 v200, v200
	v_exp_f32_e32 v226, v226
	v_exp_f32_e32 v236, v236
	v_exp_f32_e32 v239, v239
	v_add_f32_e32 v192, 1.0, v192
	v_add_f32_e32 v194, 1.0, v194
	v_add_f32_e32 v196, 1.0, v196
	v_add_f32_e32 v198, 1.0, v198
	v_add_f32_e32 v200, 1.0, v200
	v_add_f32_e32 v226, 1.0, v226
	v_add_f32_e32 v236, 1.0, v236
	v_add_f32_e32 v239, 1.0, v239
	v_rcp_f32_e32 v192, v192
	v_rcp_f32_e32 v194, v194
	v_rcp_f32_e32 v196, v196
	v_rcp_f32_e32 v198, v198
	v_rcp_f32_e32 v200, v200
	v_rcp_f32_e32 v226, v226
	v_rcp_f32_e32 v236, v236
	v_rcp_f32_e32 v239, v239
	v_mul_f32_e32 v94, v94, v192
	v_mul_f32_e32 v95, v95, v194
	v_mul_f32_e32 v96, v96, v196
	v_mul_f32_e32 v97, v97, v198
	v_mul_f32_e32 v86, v86, v200
	v_mul_f32_e32 v87, v87, v226
	v_mul_f32_e32 v88, v88, v236
	v_mul_f32_e32 v89, v89, v239
	v_mul_f32_e32 v94, v90, v94
	v_mul_f32_e32 v95, v91, v95
	v_mul_f32_e32 v96, v92, v96
	v_mul_f32_e32 v97, v93, v97
	v_mul_f32_e32 v86, v82, v86
	v_mul_f32_e32 v87, v83, v87
	v_mul_f32_e32 v88, v84, v88
	v_mul_f32_e32 v89, v85, v89
	v_cvt_pk_bf16_f32 v202, v94, v95
	v_cvt_pk_bf16_f32 v203, v96, v97
	v_cvt_pk_bf16_f32 v204, v86, v87
	v_cvt_pk_bf16_f32 v205, v88, v89
	global_store_dwordx4 v188, v[202:205], s[12:13]
	v_add_u32_e32 v188, 0x2c000, v188
	v_pk_fma_f32 v[78:79], v[78:79], v[232:233], v[138:139] op_sel_hi:[1,0,1]
	v_pk_fma_f32 v[74:75], v[74:75], v[232:233], v[240:241] op_sel_hi:[1,0,1]
	v_pk_fma_f32 v[80:81], v[80:81], v[232:233], v[140:141] op_sel_hi:[1,0,1]
	v_pk_fma_f32 v[76:77], v[76:77], v[232:233], v[242:243] op_sel_hi:[1,0,1]
	v_pk_fma_f32 v[70:71], v[70:71], v[232:233], v[142:143] op_sel_hi:[1,0,1]
	v_pk_fma_f32 v[66:67], v[66:67], v[232:233], v[244:245] op_sel_hi:[1,0,1]
	v_pk_fma_f32 v[72:73], v[72:73], v[232:233], v[144:145] op_sel_hi:[1,0,1]
	v_pk_fma_f32 v[68:69], v[68:69], v[232:233], v[246:247] op_sel_hi:[1,0,1]
	v_mul_f32_e32 v192, 0xbfb8aa3b, v78
	v_mul_f32_e32 v194, 0xbfb8aa3b, v79
	v_mul_f32_e32 v196, 0xbfb8aa3b, v80
	v_mul_f32_e32 v198, 0xbfb8aa3b, v81
	v_mul_f32_e32 v200, 0xbfb8aa3b, v70
	v_mul_f32_e32 v226, 0xbfb8aa3b, v71
	v_mul_f32_e32 v236, 0xbfb8aa3b, v72
	v_mul_f32_e32 v239, 0xbfb8aa3b, v73
	v_exp_f32_e32 v192, v192
	v_exp_f32_e32 v194, v194
	v_exp_f32_e32 v196, v196
	v_exp_f32_e32 v198, v198
	v_exp_f32_e32 v200, v200
	v_exp_f32_e32 v226, v226
	v_exp_f32_e32 v236, v236
	v_exp_f32_e32 v239, v239
	v_add_f32_e32 v192, 1.0, v192
	v_add_f32_e32 v194, 1.0, v194
	v_add_f32_e32 v196, 1.0, v196
	v_add_f32_e32 v198, 1.0, v198
	v_add_f32_e32 v200, 1.0, v200
	v_add_f32_e32 v226, 1.0, v226
; __device__ __forceinline__ unsigned pk2(float lo, float hi) { unsigned r; asm("v_cvt_pk_bf16_f32 %0, %1, %2" : "=v"(r) : "v"(lo), "v"(hi)); return r; }
;     __device__ __forceinline__ void operator()(const f32x4 (&acc)[2][2][4][2], const Unit& u, int wr, int wc, int fr_, int fq_) const {
;     ...
;             for (int m = 0; m < 4; ++m) { const int row = row0 + ai * HALF + m * 16; const float r = rs[ai][m];
;                 unsigned hw[4];
; #pragma unroll
;                 for (int n = 0; n < 2; ++n) { const f32x4 g = acc[ai][0][m][n] * r + sh[0][n], up = acc[ai][1][m][n] * r + sh[1][n];
;                     float h[4];
; #pragma unroll
;                     for (int e = 0; e < 4; ++e) h[e] = g[e] * __builtin_amdgcn_rcpf(1.0f + __builtin_amdgcn_exp2f(-g[e] * LOG2E)) * up[e];
;                     hw[2 * n] = pk2(h[0], h[1]); hw[2 * n + 1] = pk2(h[2], h[3]); }
;                 u32x4 w; w.x = hw[0]; w.y = hw[1]; w.z = hw[2]; w.w = hw[3];
;                 *(u32x4*)(HB + (size_t)row * FF + u.pn * HALF + wc * 32 + 8 * fq) = w; }
	v_add_f32_e32 v236, 1.0, v236
	v_add_f32_e32 v239, 1.0, v239
	v_rcp_f32_e32 v192, v192
	v_rcp_f32_e32 v194, v194
	v_rcp_f32_e32 v196, v196
	v_rcp_f32_e32 v198, v198
	v_rcp_f32_e32 v200, v200
	v_rcp_f32_e32 v226, v226
	v_rcp_f32_e32 v236, v236
	v_rcp_f32_e32 v239, v239
	v_mul_f32_e32 v78, v78, v192
	v_mul_f32_e32 v79, v79, v194
	v_mul_f32_e32 v80, v80, v196
	v_mul_f32_e32 v81, v81, v198
	v_mul_f32_e32 v70, v70, v200
	v_mul_f32_e32 v71, v71, v226
	v_mul_f32_e32 v72, v72, v236
	v_mul_f32_e32 v73, v73, v239
	v_mul_f32_e32 v78, v74, v78
	v_mul_f32_e32 v79, v75, v79
	v_mul_f32_e32 v80, v76, v80
	v_mul_f32_e32 v81, v77, v81
	v_mul_f32_e32 v70, v66, v70
	v_mul_f32_e32 v71, v67, v71
	v_mul_f32_e32 v72, v68, v72
	v_mul_f32_e32 v73, v69, v73
	v_cvt_pk_bf16_f32 v210, v78, v79
	v_cvt_pk_bf16_f32 v211, v80, v81
	v_cvt_pk_bf16_f32 v212, v70, v71
	v_cvt_pk_bf16_f32 v213, v72, v73
	global_store_dwordx4 v188, v[210:213], s[12:13]
	v_add_u32_e32 v188, 0xdc000, v188
	v_pk_fma_f32 v[62:63], v[62:63], v[162:163], v[138:139] op_sel_hi:[1,0,1]
	v_pk_fma_f32 v[58:59], v[58:59], v[162:163], v[240:241] op_sel_hi:[1,0,1]
	v_pk_fma_f32 v[64:65], v[64:65], v[162:163], v[140:141] op_sel_hi:[1,0,1]
	v_pk_fma_f32 v[60:61], v[60:61], v[162:163], v[242:243] op_sel_hi:[1,0,1]
	v_pk_fma_f32 v[54:55], v[54:55], v[162:163], v[142:143] op_sel_hi:[1,0,1]
	v_pk_fma_f32 v[50:51], v[50:51], v[162:163], v[244:245] op_sel_hi:[1,0,1]
	v_pk_fma_f32 v[56:57], v[56:57], v[162:163], v[144:145] op_sel_hi:[1,0,1]
	v_pk_fma_f32 v[52:53], v[52:53], v[162:163], v[246:247] op_sel_hi:[1,0,1]
	v_mul_f32_e32 v192, 0xbfb8aa3b, v62
	v_mul_f32_e32 v194, 0xbfb8aa3b, v63
	v_mul_f32_e32 v196, 0xbfb8aa3b, v64
	v_mul_f32_e32 v198, 0xbfb8aa3b, v65
	v_mul_f32_e32 v200, 0xbfb8aa3b, v54
	v_mul_f32_e32 v226, 0xbfb8aa3b, v55
	v_mul_f32_e32 v236, 0xbfb8aa3b, v56
	v_mul_f32_e32 v239, 0xbfb8aa3b, v57
	v_exp_f32_e32 v192, v192
	v_exp_f32_e32 v194, v194
	v_exp_f32_e32 v196, v196
	v_exp_f32_e32 v198, v198
	v_exp_f32_e32 v200, v200
	v_exp_f32_e32 v226, v226
	v_exp_f32_e32 v236, v236
	v_exp_f32_e32 v239, v239
	v_add_f32_e32 v192, 1.0, v192
	v_add_f32_e32 v194, 1.0, v194
	v_add_f32_e32 v196, 1.0, v196
	v_add_f32_e32 v198, 1.0, v198
	v_add_f32_e32 v200, 1.0, v200
	v_add_f32_e32 v226, 1.0, v226
	v_add_f32_e32 v236, 1.0, v236
	v_add_f32_e32 v239, 1.0, v239
	v_rcp_f32_e32 v192, v192
	v_rcp_f32_e32 v194, v194
	v_rcp_f32_e32 v196, v196
	v_rcp_f32_e32 v198, v198
	v_rcp_f32_e32 v200, v200
	v_rcp_f32_e32 v226, v226
	v_rcp_f32_e32 v236, v236
	v_rcp_f32_e32 v239, v239
	v_mul_f32_e32 v62, v62, v192
	v_mul_f32_e32 v63, v63, v194
	v_mul_f32_e32 v64, v64, v196
	v_mul_f32_e32 v65, v65, v198
	v_mul_f32_e32 v54, v54, v200
	v_mul_f32_e32 v55, v55, v226
	v_mul_f32_e32 v56, v56, v236
	v_mul_f32_e32 v57, v57, v239
	v_mul_f32_e32 v62, v58, v62
	v_mul_f32_e32 v63, v59, v63
	v_mul_f32_e32 v64, v60, v64
	v_mul_f32_e32 v65, v61, v65
	v_mul_f32_e32 v54, v50, v54
	v_mul_f32_e32 v55, v51, v55
	v_mul_f32_e32 v56, v52, v56
	v_mul_f32_e32 v57, v53, v57
	v_cvt_pk_bf16_f32 v202, v62, v63
	v_cvt_pk_bf16_f32 v203, v64, v65
	v_cvt_pk_bf16_f32 v204, v54, v55
	v_cvt_pk_bf16_f32 v205, v56, v57
	global_store_dwordx4 v188, v[202:205], s[12:13]
	v_add_u32_e32 v188, 0x2c000, v188
	v_pk_fma_f32 v[46:47], v[46:47], v[170:171], v[138:139] op_sel_hi:[1,0,1]
	v_pk_fma_f32 v[42:43], v[42:43], v[170:171], v[240:241] op_sel_hi:[1,0,1]
	v_pk_fma_f32 v[48:49], v[48:49], v[170:171], v[140:141] op_sel_hi:[1,0,1]
	v_pk_fma_f32 v[44:45], v[44:45], v[170:171], v[242:243] op_sel_hi:[1,0,1]
	v_pk_fma_f32 v[38:39], v[38:39], v[170:171], v[142:143] op_sel_hi:[1,0,1]
	v_pk_fma_f32 v[34:35], v[34:35], v[170:171], v[244:245] op_sel_hi:[1,0,1]
	v_pk_fma_f32 v[40:41], v[40:41], v[170:171], v[144:145] op_sel_hi:[1,0,1]
	v_pk_fma_f32 v[36:37], v[36:37], v[170:171], v[246:247] op_sel_hi:[1,0,1]
	v_mul_f32_e32 v192, 0xbfb8aa3b, v46
	v_mul_f32_e32 v194, 0xbfb8aa3b, v47
	v_mul_f32_e32 v196, 0xbfb8aa3b, v48
	v_mul_f32_e32 v198, 0xbfb8aa3b, v49
	v_mul_f32_e32 v200, 0xbfb8aa3b, v38
	v_mul_f32_e32 v226, 0xbfb8aa3b, v39
	v_mul_f32_e32 v236, 0xbfb8aa3b, v40
	v_mul_f32_e32 v239, 0xbfb8aa3b, v41
	v_exp_f32_e32 v192, v192
	v_exp_f32_e32 v194, v194
	v_exp_f32_e32 v196, v196
	v_exp_f32_e32 v198, v198
	v_exp_f32_e32 v200, v200
	v_exp_f32_e32 v226, v226
	v_exp_f32_e32 v236, v236
	v_exp_f32_e32 v239, v239
	v_add_f32_e32 v192, 1.0, v192
	v_add_f32_e32 v194, 1.0, v194
	v_add_f32_e32 v196, 1.0, v196
	v_add_f32_e32 v198, 1.0, v198
	v_add_f32_e32 v200, 1.0, v200
	v_add_f32_e32 v226, 1.0, v226
	v_add_f32_e32 v236, 1.0, v236
	v_add_f32_e32 v239, 1.0, v239
	v_rcp_f32_e32 v192, v192
	v_rcp_f32_e32 v194, v194
	v_rcp_f32_e32 v196, v196
	v_rcp_f32_e32 v198, v198
	v_rcp_f32_e32 v200, v200
	v_rcp_f32_e32 v226, v226
	v_rcp_f32_e32 v236, v236
	v_rcp_f32_e32 v239, v239
	v_mul_f32_e32 v46, v46, v192
	v_mul_f32_e32 v47, v47, v194
	v_mul_f32_e32 v48, v48, v196
	v_mul_f32_e32 v49, v49, v198
	v_mul_f32_e32 v38, v38, v200
	v_mul_f32_e32 v39, v39, v226
	v_mul_f32_e32 v40, v40, v236
	v_mul_f32_e32 v41, v41, v239
	v_mul_f32_e32 v46, v42, v46
; #define PG8_BAR __builtin_amdgcn_s_barrier()
; __device__ __forceinline__ unsigned pk2(float lo, float hi) { unsigned r; asm("v_cvt_pk_bf16_f32 %0, %1, %2" : "=v"(r) : "v"(lo), "v"(hi)); return r; }
; template <class Epi, class Sched, bool ALIGN_EPI = false, bool SP2 = false>
; __device__ __forceinline__ void gemm_phase(PG8_LAS unsigned char* lds, const Gemm g, const Sched& S, const Epi& E, const int wave_s) {
;     ...
;         if constexpr (ALIGN_EPI) { if (wr == 0) PG8_BAR; }
;         if constexpr (!Epi::AFTER_DRAIN) { E(acc, cur, wr, wc, fr, fq); S.done(cur); }
;         if (!has_next) break;
; #pragma unroll
;         for (int a = 0; a < 2; ++a)
; #pragma unroll
;             for (int b = 0; b < 2; ++b)
; #pragma unroll
;                 for (int m = 0; m < 4; ++m)
; #pragma unroll
;                     for (int n = 0; n < 2; ++n) acc[a][b][m][n] = (f32x4){0.f, 0.f, 0.f, 0.f};
;         cur = nxt; cA = nA; cB = nB; ++ui;
;         if constexpr (ALIGN_EPI) { if (wr == 1) PG8_BAR; }
;     }
;     __device__ __forceinline__ void operator()(const f32x4 (&acc)[2][2][4][2], const Unit& u, int wr, int wc, int fr_, int fq_) const {
;     ...
;             for (int m = 0; m < 4; ++m) { const int row = row0 + ai * HALF + m * 16; const float r = rs[ai][m];
;                 unsigned hw[4];
; #pragma unroll
;                 for (int n = 0; n < 2; ++n) { const f32x4 g = acc[ai][0][m][n] * r + sh[0][n], up = acc[ai][1][m][n] * r + sh[1][n];
;                     float h[4];
; #pragma unroll
;                     for (int e = 0; e < 4; ++e) h[e] = g[e] * __builtin_amdgcn_rcpf(1.0f + __builtin_amdgcn_exp2f(-g[e] * LOG2E)) * up[e];
;                     hw[2 * n] = pk2(h[0], h[1]); hw[2 * n + 1] = pk2(h[2], h[3]); }
;                 u32x4 w; w.x = hw[0]; w.y = hw[1]; w.z = hw[2]; w.w = hw[3];
;                 *(u32x4*)(HB + (size_t)row * FF + u.pn * HALF + wc * 32 + 8 * fq) = w; }
	v_mul_f32_e32 v47, v43, v47
	v_mul_f32_e32 v48, v44, v48
	v_mul_f32_e32 v49, v45, v49
	v_mul_f32_e32 v38, v34, v38
	v_mul_f32_e32 v39, v35, v39
	v_mul_f32_e32 v40, v36, v40
	v_mul_f32_e32 v41, v37, v41
	v_cvt_pk_bf16_f32 v210, v46, v47
	v_cvt_pk_bf16_f32 v211, v48, v49
	v_cvt_pk_bf16_f32 v212, v38, v39
	v_cvt_pk_bf16_f32 v213, v40, v41
	global_store_dwordx4 v188, v[210:213], s[12:13]
	v_add_u32_e32 v188, 0x2c000, v188
	v_pk_fma_f32 v[30:31], v[30:31], v[178:179], v[138:139] op_sel_hi:[1,0,1]
	v_pk_fma_f32 v[26:27], v[26:27], v[178:179], v[240:241] op_sel_hi:[1,0,1]
	v_pk_fma_f32 v[32:33], v[32:33], v[178:179], v[140:141] op_sel_hi:[1,0,1]
	v_pk_fma_f32 v[28:29], v[28:29], v[178:179], v[242:243] op_sel_hi:[1,0,1]
	v_pk_fma_f32 v[22:23], v[22:23], v[178:179], v[142:143] op_sel_hi:[1,0,1]
	v_pk_fma_f32 v[18:19], v[18:19], v[178:179], v[244:245] op_sel_hi:[1,0,1]
	v_pk_fma_f32 v[24:25], v[24:25], v[178:179], v[144:145] op_sel_hi:[1,0,1]
	v_pk_fma_f32 v[20:21], v[20:21], v[178:179], v[246:247] op_sel_hi:[1,0,1]
	v_mul_f32_e32 v192, 0xbfb8aa3b, v30
	v_mul_f32_e32 v194, 0xbfb8aa3b, v31
	v_mul_f32_e32 v196, 0xbfb8aa3b, v32
	v_mul_f32_e32 v198, 0xbfb8aa3b, v33
	v_mul_f32_e32 v200, 0xbfb8aa3b, v22
	v_mul_f32_e32 v226, 0xbfb8aa3b, v23
	v_mul_f32_e32 v236, 0xbfb8aa3b, v24
	v_mul_f32_e32 v239, 0xbfb8aa3b, v25
	v_exp_f32_e32 v192, v192
	v_exp_f32_e32 v194, v194
	v_exp_f32_e32 v196, v196
	v_exp_f32_e32 v198, v198
	v_exp_f32_e32 v200, v200
	v_exp_f32_e32 v226, v226
	v_exp_f32_e32 v236, v236
	v_exp_f32_e32 v239, v239
	v_add_f32_e32 v192, 1.0, v192
	v_add_f32_e32 v194, 1.0, v194
	v_add_f32_e32 v196, 1.0, v196
	v_add_f32_e32 v198, 1.0, v198
	v_add_f32_e32 v200, 1.0, v200
	v_add_f32_e32 v226, 1.0, v226
	v_add_f32_e32 v236, 1.0, v236
	v_add_f32_e32 v239, 1.0, v239
	v_rcp_f32_e32 v192, v192
	v_rcp_f32_e32 v194, v194
	v_rcp_f32_e32 v196, v196
	v_rcp_f32_e32 v198, v198
	v_rcp_f32_e32 v200, v200
	v_rcp_f32_e32 v226, v226
	v_rcp_f32_e32 v236, v236
	v_rcp_f32_e32 v239, v239
	v_mul_f32_e32 v30, v30, v192
	v_mul_f32_e32 v31, v31, v194
	v_mul_f32_e32 v32, v32, v196
	v_mul_f32_e32 v33, v33, v198
	v_mul_f32_e32 v22, v22, v200
	v_mul_f32_e32 v23, v23, v226
	v_mul_f32_e32 v24, v24, v236
	v_mul_f32_e32 v25, v25, v239
	v_mul_f32_e32 v30, v26, v30
	v_mul_f32_e32 v31, v27, v31
	v_mul_f32_e32 v32, v28, v32
	v_mul_f32_e32 v33, v29, v33
	v_mul_f32_e32 v22, v18, v22
	v_mul_f32_e32 v23, v19, v23
	v_mul_f32_e32 v24, v20, v24
	v_mul_f32_e32 v25, v21, v25
	v_cvt_pk_bf16_f32 v202, v30, v31
	v_cvt_pk_bf16_f32 v203, v32, v33
	v_cvt_pk_bf16_f32 v204, v22, v23
	v_cvt_pk_bf16_f32 v205, v24, v25
	global_store_dwordx4 v188, v[202:205], s[12:13]
	v_add_u32_e32 v188, 0x2c000, v188
	v_pk_fma_f32 v[14:15], v[14:15], v[134:135], v[138:139] op_sel_hi:[1,0,1]
	v_pk_fma_f32 v[10:11], v[10:11], v[134:135], v[240:241] op_sel_hi:[1,0,1]
	v_pk_fma_f32 v[16:17], v[16:17], v[134:135], v[140:141] op_sel_hi:[1,0,1]
	v_pk_fma_f32 v[12:13], v[12:13], v[134:135], v[242:243] op_sel_hi:[1,0,1]
	v_pk_fma_f32 v[6:7], v[6:7], v[134:135], v[142:143] op_sel_hi:[1,0,1]
	v_pk_fma_f32 v[2:3], v[2:3], v[134:135], v[244:245] op_sel_hi:[1,0,1]
	v_pk_fma_f32 v[8:9], v[8:9], v[134:135], v[144:145] op_sel_hi:[1,0,1]
	v_pk_fma_f32 v[4:5], v[4:5], v[134:135], v[246:247] op_sel_hi:[1,0,1]
	v_mul_f32_e32 v192, 0xbfb8aa3b, v14
	v_mul_f32_e32 v194, 0xbfb8aa3b, v15
	v_mul_f32_e32 v196, 0xbfb8aa3b, v16
	v_mul_f32_e32 v198, 0xbfb8aa3b, v17
	v_mul_f32_e32 v200, 0xbfb8aa3b, v6
	v_mul_f32_e32 v226, 0xbfb8aa3b, v7
	v_mul_f32_e32 v236, 0xbfb8aa3b, v8
	v_mul_f32_e32 v239, 0xbfb8aa3b, v9
	v_exp_f32_e32 v192, v192
	v_exp_f32_e32 v194, v194
	v_exp_f32_e32 v196, v196
	v_exp_f32_e32 v198, v198
	v_exp_f32_e32 v200, v200
	v_exp_f32_e32 v226, v226
	v_exp_f32_e32 v236, v236
	v_exp_f32_e32 v239, v239
	v_add_f32_e32 v192, 1.0, v192
	v_add_f32_e32 v194, 1.0, v194
	v_add_f32_e32 v196, 1.0, v196
	v_add_f32_e32 v198, 1.0, v198
	v_add_f32_e32 v200, 1.0, v200
	v_add_f32_e32 v226, 1.0, v226
	v_add_f32_e32 v236, 1.0, v236
	v_add_f32_e32 v239, 1.0, v239
	v_rcp_f32_e32 v192, v192
	v_rcp_f32_e32 v194, v194
	v_rcp_f32_e32 v196, v196
	v_rcp_f32_e32 v198, v198
	v_rcp_f32_e32 v200, v200
	v_rcp_f32_e32 v226, v226
	v_rcp_f32_e32 v236, v236
	v_rcp_f32_e32 v239, v239
	v_mul_f32_e32 v14, v14, v192
	v_mul_f32_e32 v15, v15, v194
	v_mul_f32_e32 v16, v16, v196
	v_mul_f32_e32 v17, v17, v198
	v_mul_f32_e32 v6, v6, v200
	v_mul_f32_e32 v7, v7, v226
	v_mul_f32_e32 v8, v8, v236
	v_mul_f32_e32 v9, v9, v239
	v_mul_f32_e32 v14, v10, v14
	v_mul_f32_e32 v15, v11, v15
	v_mul_f32_e32 v16, v12, v16
	v_mul_f32_e32 v17, v13, v17
	v_mul_f32_e32 v6, v2, v6
	v_mul_f32_e32 v7, v3, v7
	v_mul_f32_e32 v8, v4, v8
	v_mul_f32_e32 v9, v5, v9
	v_cvt_pk_bf16_f32 v210, v14, v15
	v_cvt_pk_bf16_f32 v211, v16, v17
	v_cvt_pk_bf16_f32 v212, v6, v7
	v_cvt_pk_bf16_f32 v213, v8, v9
	global_store_dwordx4 v188, v[210:213], s[12:13]
	s_waitcnt lgkmcnt(0)
	s_andn2_b64 vcc, exec, s[36:37]
	s_mov_b64 s[38:39], -1
	s_cbranch_vccnz .LBB0_1154
	s_andn2_b64 vcc, exec, s[42:43]
	s_cbranch_vccnz .LBB0_1153
	s_barrier
	s_branch .LBB0_1153
